# global-attention loop unrolled x2 with 2-tile-deep K/V register prefetch plus early V-fragment LDS reads
# speedup vs baseline: 1.0163x; 1.0080x over previous
.LBB0_1273:
	s_andn2_b64 vcc, exec, s[0:1]
	s_cbranch_vccnz .LBB0_1287
	s_lshl_b32 s0, s22, 1
	s_addk_i32 s0, 0xfeb0
	v_mov_b32_e32 v20, v201
	v_add_u32_e32 v8, s0, v149
	v_lshlrev_b32_e32 v0, 6, v8
	v_lshrrev_b32_e32 v6, 1, v20
	v_and_b32_e32 v2, 32, v6
	s_movk_i32 s0, 0xfc0
	v_ashrrev_i32_e32 v106, 7, v8
	v_bfe_u32 v5, v8, 6, 1
	v_and_or_b32 v0, v0, s0, v2
	v_mov_b64_e32 v[2:3], s[42:43]
	s_mov_b32 s0, 0x220000
	v_mad_i64_i32 v[2:3], s[0:1], v106, s0, v[2:3]
	v_lshlrev_b32_e32 v4, 7, v5
	v_and_or_b32 v110, v6, 64, v4
	v_mov_b64_e32 v[6:7], s[58:59]
	s_mov_b32 s0, 0x110000
	v_add_u32_e32 v108, 0x100, v0
	v_lshlrev_b32_e32 v0, 1, v110
	v_mad_i64_i32 v[6:7], s[0:1], v106, s0, v[6:7]
	v_and_b32_e32 v107, 15, v20
	v_bfe_u32 v21, v20, 4, 2
	v_lshl_add_u64 v[2:3], v[2:3], 0, v[0:1]
	v_lshlrev_b32_e32 v0, 6, v5
	v_mov_b32_e32 v5, v1
	s_movk_i32 s0, 0xff80
	v_lshl_add_u64 v[4:5], v[6:7], 0, v[4:5]
	v_and_or_b32 v6, v8, s0, v0
	v_or_b32_e32 v7, v108, v107
	v_lshlrev_b32_e32 v0, 4, v21
	v_lshl_add_u64 v[2:3], v[2:3], 0, v[0:1]
	v_lshlrev_b32_e32 v0, 9, v7
	v_lshl_add_u64 v[2:3], v[2:3], 0, v[0:1]
	s_movk_i32 s0, 0x2000
	global_load_dwordx4 v[46:49], v[2:3], off
	global_load_dwordx4 v[42:45], v[2:3], off offset:64
	v_add_co_u32_e32 v2, vcc, s0, v2
	v_and_b32_e32 v22, 7, v20
	s_nop 0
	v_addc_co_u32_e32 v3, vcc, 0, v3, vcc
	global_load_dwordx4 v[50:53], v[2:3], off
	global_load_dwordx4 v[54:57], v[2:3], off offset:64
	v_mov_b64_e32 v[2:3], s[44:45]
	v_bfe_u32 v126, v20, 3, 5
	v_lshlrev_b32_e32 v114, 4, v22
	v_mov_b32_e32 v115, v1
	v_mad_i64_i32 v[2:3], s[0:1], v6, s85, v[2:3]
	v_lshl_add_u64 v[116:117], v[4:5], 0, v[114:115]
	v_lshlrev_b32_e32 v0, 8, v126
	v_or_b32_e32 v23, 32, v126
	v_lshl_add_u64 v[18:19], v[2:3], 0, v[114:115]
	v_lshl_add_u64 v[2:3], v[116:117], 0, v[0:1]
	v_lshlrev_b32_e32 v0, 8, v23
	v_mad_u64_u32 v[6:7], s[0:1], v126, s85, v[18:19]
	v_lshl_add_u64 v[10:11], v[116:117], 0, v[0:1]
	v_mad_u64_u32 v[14:15], s[0:1], v23, s85, v[18:19]
	v_mov_b32 v122, 0xf149f2ca
	global_load_dwordx4 v[2:5], v[2:3], off
	s_nop 0
	global_load_dwordx4 v[6:9], v[6:7], off
	s_nop 0
	global_load_dwordx4 v[10:13], v[10:11], off
	s_nop 0
	global_load_dwordx4 v[14:17], v[14:15], off
	v_lshrrev_b32_e32 v26, 3, v20
	v_lshrrev_b32_e32 v25, 4, v20
	v_xor_b32_e32 v20, v26, v20
	v_lshlrev_b32_e32 v20, 4, v20
	v_and_b32_e32 v132, 0x70, v20
	v_lshlrev_b32_e32 v112, 3, v21
	v_lshlrev_b32_e32 v127, 7, v126
	v_bitop3_b32 v21, v21, v22, 4 bitop3:0x36
	v_add_u32_e32 v20, v150, v132
	v_and_b32_e32 v24, 64, v208
	v_mul_u32_u24_e32 v128, 0x90, v126
	v_lshlrev_b32_e32 v131, 7, v23
	v_lshlrev_b32_e32 v129, 4, v21
	v_add_u32_e32 v21, v20, v127
	v_xor_b32_e32 v0, 16, v208
	v_bitop3_b32 v25, v25, v22, 3 bitop3:0x6c
	v_add3_u32 v22, v150, v114, v128
	v_add_u32_e32 v20, v20, v131
	v_lshlrev_b32_e32 v130, 4, v25
	v_mov_b32_e32 v38, 0
	s_mov_b32 s0, 0
	v_lshlrev_b32_e32 v115, 7, v107
	v_mov_b32_e32 v123, v122
	v_mul_u32_u24_e32 v109, 0x90, v107
	v_mov_b32_e32 v39, v38
	v_mov_b32_e32 v40, v38
	v_mov_b32_e32 v41, v38
	v_mov_b32_e32 v34, v38
	v_mov_b32_e32 v35, v38
	v_mov_b32_e32 v36, v38
	v_mov_b32_e32 v37, v38
	s_waitcnt vmcnt(0) lgkmcnt(0)
	ds_write_b128 v21, v[2:5]
	ds_write_b128 v22, v[6:9] offset:8192
	ds_write_b128 v20, v[10:13]
	ds_write_b128 v22, v[14:17] offset:12800
	v_add_u32_e32 v2, 64, v24
	v_cmp_lt_i32_e32 vcc, v0, v2
	v_mov_b32_e32 v3, v1
	s_waitcnt lgkmcnt(0)
	v_cndmask_b32_e32 v0, v208, v0, vcc
	v_lshlrev_b32_e32 v111, 2, v0
	v_xor_b32_e32 v0, 32, v208
	v_cmp_lt_i32_e32 vcc, v0, v2
	v_mov_b32_e32 v2, v1
	s_barrier
	v_cndmask_b32_e32 v0, v208, v0, vcc
	v_lshlrev_b32_e32 v113, 2, v0
	v_mul_u32_u24_e32 v0, 0x1100, v126
	v_lshlrev_b32_e32 v0, 1, v0
	v_lshl_add_u64 v[120:121], v[18:19], 0, v[0:1]
	v_mov_b32_e32 v0, v1
	v_mov_b64_e32 v[20:21], v[2:3]
	v_mov_b64_e32 v[24:25], v[2:3]
	v_mov_b64_e32 v[28:29], v[2:3]
	v_mov_b64_e32 v[32:33], v[2:3]
	v_mov_b64_e32 v[12:13], v[2:3]
	v_mov_b64_e32 v[16:17], v[2:3]
	v_mov_b64_e32 v[8:9], v[2:3]
	v_mov_b64_e32 v[18:19], v[0:1]
	v_mov_b64_e32 v[22:23], v[0:1]
	v_mov_b64_e32 v[26:27], v[0:1]
	v_mov_b64_e32 v[30:31], v[0:1]
	v_mov_b64_e32 v[10:11], v[0:1]
	v_mov_b64_e32 v[14:15], v[0:1]
	v_mov_b64_e32 v[6:7], v[0:1]
	v_mov_b64_e32 v[4:5], v[2:3]
	v_mov_b64_e32 v[2:3], v[0:1]
	s_mov_b32 s1, 1
	v_lshl_or_b32 v68, s1, 6, v126
	v_lshlrev_b32_e32 v0, 8, v68
	s_lshl_b32 s56, s1, 7
	v_lshl_add_u64 v[58:59], v[116:117], 0, v[0:1]
	v_lshl_add_u64 v[66:67], v[120:121], 0, s[56:57]
	v_or_b32_e32 v0, 32, v68
	s_mov_b32 s1, 0x44000
	v_lshlrev_b64 v[68:69], 8, v[0:1]
	v_add_co_u32_e32 v70, vcc, s1, v66
	v_lshl_add_u64 v[68:69], v[116:117], 0, v[68:69]
	s_nop 0
	v_addc_co_u32_e32 v71, vcc, 0, v67, vcc
	global_load_dwordx4 v[58:61], v[58:59], off
	s_nop 0
	global_load_dwordx4 v[62:65], v[66:67], off
	s_nop 0
	global_load_dwordx4 v[66:69], v[68:69], off
	s_nop 0
	global_load_dwordx4 v[70:73], v[70:71], off
.LBB0_1275:
	s_bitcmp1_b32 s0, 0
	s_mov_b32 s1, s0
	s_cselect_b32 s2, 0x4400, 0
	s_add_i32 s0, s0, 1
	s_add_i32 s1, s0, 1
	s_min_u32 s1, s1, 0x43
	v_lshl_or_b32 v238, s1, 6, v126
	v_lshlrev_b32_e32 v0, 8, v238
	s_lshl_b32 s56, s1, 7
	v_lshl_add_u64 v[228:229], v[116:117], 0, v[0:1]
	v_lshl_add_u64 v[236:237], v[120:121], 0, s[56:57]
	v_or_b32_e32 v0, 32, v238
	s_mov_b32 s1, 0x44000
	v_lshlrev_b64 v[238:239], 8, v[0:1]
	v_add_co_u32_e32 v240, vcc, s1, v236
	v_lshl_add_u64 v[238:239], v[116:117], 0, v[238:239]
	s_nop 0
	v_addc_co_u32_e32 v241, vcc, 0, v237, vcc
	global_load_dwordx4 v[228:231], v[228:229], off
	s_nop 0
	global_load_dwordx4 v[232:235], v[236:237], off
	s_nop 0
	global_load_dwordx4 v[236:239], v[238:239], off
	s_nop 0
	global_load_dwordx4 v[240:243], v[240:241], off
	v_add_u32_e32 v0, s2, v150
	s_setprio 1
	v_add_u32_e32 v86, v0, v115
	v_add_u32_e32 v102, v86, v130
	ds_read_b128 v[74:77], v102
	ds_read_b128 v[82:85], v102 offset:2048
	v_add_u32_e32 v103, v86, v129
	ds_read_b128 v[86:89], v103
	ds_read_b128 v[98:101], v103 offset:2048
	s_waitcnt lgkmcnt(0)
	v_mfma_f32_16x16x32_bf16 v[78:81], v[74:77], v[46:49], 0
	v_mfma_f32_16x16x32_bf16 v[74:77], v[74:77], v[50:53], 0
	v_mfma_f32_16x16x32_bf16 v[94:97], v[86:89], v[42:45], v[78:81]
	v_mfma_f32_16x16x32_bf16 v[78:81], v[86:89], v[54:57], v[74:77]
	v_mfma_f32_16x16x32_bf16 v[74:77], v[82:85], v[46:49], 0
	v_mfma_f32_16x16x32_bf16 v[90:93], v[98:101], v[42:45], v[74:77]
	v_mfma_f32_16x16x32_bf16 v[74:77], v[82:85], v[50:53], 0
	ds_read_b128 v[82:85], v102 offset:4096
	ds_read_b128 v[134:137], v102 offset:6144
	v_mfma_f32_16x16x32_bf16 v[74:77], v[98:101], v[54:57], v[74:77]
	ds_read_b128 v[98:101], v103 offset:4096
	ds_read_b128 v[138:141], v103 offset:6144
	s_waitcnt lgkmcnt(0)
	v_add3_u32 v118, v0, v109, v112
	v_add_u32_e32 v119, 0x2000, v118
	v_add_u32_e32 v124, 0x2800, v118
	ds_read2_b64 v[212:215], v119 offset1:4
	ds_read2_b64 v[216:219], v119 offset0:8 offset1:12
	ds_read2_b64 v[244:247], v124 offset0:32 offset1:36
	ds_read2_b64 v[248:251], v124 offset0:40 offset1:44
	v_mfma_f32_16x16x32_bf16 v[86:89], v[82:85], v[46:49], 0
	v_mfma_f32_16x16x32_bf16 v[82:85], v[82:85], v[50:53], 0
	v_mfma_f32_16x16x32_bf16 v[102:105], v[98:101], v[42:45], v[86:89]
	v_mfma_f32_16x16x32_bf16 v[86:89], v[98:101], v[54:57], v[82:85]
	v_mfma_f32_16x16x32_bf16 v[82:85], v[134:137], v[46:49], 0
	v_mfma_f32_16x16x32_bf16 v[98:101], v[138:141], v[42:45], v[82:85]
	v_mfma_f32_16x16x32_bf16 v[82:85], v[134:137], v[50:53], 0
	v_mfma_f32_16x16x32_bf16 v[82:85], v[138:141], v[54:57], v[82:85]
	s_setprio 0
	v_max_f32_e32 v118, v95, v95
	v_max_f32_e32 v119, v94, v94
	v_max_f32_e32 v118, v119, v118
	v_max_f32_e32 v119, v97, v97
	v_max_f32_e32 v124, v96, v96
	v_max_f32_e32 v119, v124, v119
	v_max_f32_e32 v124, v93, v93
	v_max_f32_e32 v125, v92, v92
	v_max_f32_e32 v124, v125, v124
	v_max3_f32 v124, v90, v91, v124
	v_max3_f32 v118, v118, v119, v124
	v_max_f32_e32 v119, v105, v105
	v_max_f32_e32 v124, v104, v104
	v_max_f32_e32 v119, v124, v119
	v_max_f32_e32 v124, v101, v101
	v_max_f32_e32 v125, v100, v100
	v_max_f32_e32 v124, v125, v124
	v_max3_f32 v119, v102, v103, v119
	v_max3_f32 v124, v98, v99, v124
	v_max3_f32 v118, v118, v119, v124
	ds_bpermute_b32 v119, v111, v118
	s_waitcnt lgkmcnt(0)
	v_max_f32_e32 v119, v119, v119
	v_max_f32_e32 v118, v118, v119
	ds_bpermute_b32 v119, v113, v118
	s_waitcnt lgkmcnt(0)
	v_max_f32_e32 v119, v119, v119
	v_max_f32_e32 v118, v118, v119
	v_add_f32_e32 v119, 0x41000000, v122
	v_cmp_gt_f32_e32 vcc, v118, v119
	s_cbranch_vccz .LBB0_1277
	v_max_f32_e32 v118, v118, v118
	v_max_f32_e32 v119, v122, v122
	v_max_f32_e32 v124, v119, v118
	v_sub_f32_e32 v118, v122, v124
	v_exp_f32_e32 v118, v118
	v_mov_b32_e32 v125, v123
	v_mov_b32_e32 v122, v124
	v_pk_mul_f32 v[38:39], v[38:39], v[118:119] op_sel_hi:[1,0]
	v_pk_mul_f32 v[40:41], v[40:41], v[118:119] op_sel_hi:[1,0]
	v_pk_mul_f32 v[32:33], v[32:33], v[118:119] op_sel_hi:[1,0]
	v_pk_mul_f32 v[30:31], v[30:31], v[118:119] op_sel_hi:[1,0]
	v_pk_mul_f32 v[24:25], v[24:25], v[118:119] op_sel_hi:[1,0]
	v_pk_mul_f32 v[22:23], v[22:23], v[118:119] op_sel_hi:[1,0]
	v_pk_mul_f32 v[12:13], v[12:13], v[118:119] op_sel_hi:[1,0]
	v_pk_mul_f32 v[10:11], v[10:11], v[118:119] op_sel_hi:[1,0]
	v_pk_mul_f32 v[8:9], v[8:9], v[118:119] op_sel_hi:[1,0]
	v_pk_mul_f32 v[6:7], v[6:7], v[118:119] op_sel_hi:[1,0]
	s_branch .LBB0_1278

.LBB0_1280:
	v_sub_f32_e32 v74, v74, v125
	v_exp_f32_e32 v134, v74
	v_sub_f32_e32 v74, v75, v125
	v_exp_f32_e32 v135, v74
	v_sub_f32_e32 v74, v76, v125
	v_exp_f32_e32 v136, v74
	v_sub_f32_e32 v74, v77, v125
	v_exp_f32_e32 v137, v74
	v_sub_f32_e32 v74, v86, v125
	v_exp_f32_e32 v138, v74
	v_sub_f32_e32 v74, v87, v125
	v_exp_f32_e32 v139, v74
	v_sub_f32_e32 v74, v88, v125
	v_exp_f32_e32 v140, v74
	v_sub_f32_e32 v74, v89, v125
	v_sub_f32_e32 v78, v78, v125
	v_exp_f32_e32 v141, v74
	v_sub_f32_e32 v74, v82, v125
	v_sub_f32_e32 v94, v94, v122
	v_sub_f32_e32 v95, v95, v122
	v_sub_f32_e32 v96, v96, v122
	v_sub_f32_e32 v97, v97, v122
	v_sub_f32_e32 v90, v90, v122
	v_sub_f32_e32 v91, v91, v122
	v_sub_f32_e32 v92, v92, v122
	v_sub_f32_e32 v93, v93, v122
	v_sub_f32_e32 v102, v102, v122
	v_sub_f32_e32 v103, v103, v122
	v_sub_f32_e32 v104, v104, v122
	v_sub_f32_e32 v105, v105, v122
	v_sub_f32_e32 v98, v98, v122
	v_sub_f32_e32 v99, v99, v122
	v_sub_f32_e32 v100, v100, v122
	v_sub_f32_e32 v101, v101, v122
	v_exp_f32_e32 v122, v78
	v_sub_f32_e32 v78, v79, v125
	v_exp_f32_e32 v142, v74
	v_sub_f32_e32 v74, v83, v125
	v_exp_f32_e32 v123, v78
	v_sub_f32_e32 v78, v80, v125
	v_exp_f32_e32 v143, v74
	v_sub_f32_e32 v74, v84, v125
	s_mov_b32 s38, s36
	s_mov_b32 s39, s36
	v_mov_b64_e32 v[118:119], v[124:125]
	v_exp_f32_e32 v124, v78
	v_sub_f32_e32 v78, v81, v125
	v_exp_f32_e32 v144, v74
	v_sub_f32_e32 v74, v85, v125
	s_mov_b32 s37, s36
	v_mov_b64_e32 v[84:85], s[38:39]
	v_exp_f32_e32 v94, v94
	v_exp_f32_e32 v95, v95
	v_exp_f32_e32 v96, v96
	v_exp_f32_e32 v97, v97
	v_exp_f32_e32 v90, v90
	v_exp_f32_e32 v91, v91
	v_exp_f32_e32 v92, v92
	v_exp_f32_e32 v93, v93
	v_exp_f32_e32 v133, v78
	v_mov_b64_e32 v[82:83], s[36:37]
	v_exp_f32_e32 v102, v102
	v_exp_f32_e32 v103, v103
	v_exp_f32_e32 v104, v104
	v_exp_f32_e32 v105, v105
	v_exp_f32_e32 v98, v98
	v_exp_f32_e32 v99, v99
	v_exp_f32_e32 v100, v100
	v_exp_f32_e32 v101, v101
	v_exp_f32_e32 v125, v74
	v_cvt_pk_bf16_f32 v74, v94, v95
	v_cvt_pk_bf16_f32 v75, v96, v97
	v_cvt_pk_bf16_f32 v76, v90, v91
	v_cvt_pk_bf16_f32 v77, v92, v93
	v_cvt_pk_bf16_f32 v86, v122, v123
	v_cvt_pk_bf16_f32 v87, v124, v133
	v_cvt_pk_bf16_f32 v88, v134, v135
	v_cvt_pk_bf16_f32 v89, v136, v137
	v_mfma_f32_16x16x32_bf16 v[38:41], v[82:85], v[74:77], v[38:41]
	v_cvt_pk_bf16_f32 v78, v102, v103
	v_cvt_pk_bf16_f32 v79, v104, v105
	v_cvt_pk_bf16_f32 v80, v98, v99
	v_mfma_f32_16x16x32_bf16 v[34:37], v[82:85], v[86:89], v[34:37]
	v_cvt_pk_bf16_f32 v81, v100, v101
	v_cvt_pk_bf16_f32 v90, v138, v139
	v_cvt_pk_bf16_f32 v91, v140, v141
	v_cvt_pk_bf16_f32 v92, v142, v143
	v_cvt_pk_bf16_f32 v93, v144, v125
	v_mfma_f32_16x16x32_bf16 v[38:41], v[82:85], v[78:81], v[38:41]
	s_nop 0
	v_mfma_f32_16x16x32_bf16 v[34:37], v[82:85], v[90:93], v[34:37]
	s_setprio 1
	v_add3_u32 v124, v0, v109, v112
	v_add_u32_e32 v125, 0x3000, v124
	v_add_u32_e32 v124, 0x3800, v124
	ds_read2_b64 v[94:97], v125 offset0:64 offset1:68
	ds_read2_b64 v[98:101], v125 offset0:72 offset1:76
	ds_read2_b64 v[102:105], v124 offset0:96 offset1:100
	ds_read2_b64 v[134:137], v124 offset0:104 offset1:108
	s_waitcnt lgkmcnt(4)
	v_mfma_f32_16x16x32_bf16 v[30:33], v[212:215], v[74:77], v[30:33]
	v_mfma_f32_16x16x32_bf16 v[26:29], v[212:215], v[86:89], v[26:29]
	v_mfma_f32_16x16x32_bf16 v[22:25], v[244:247], v[74:77], v[22:25]
	v_mfma_f32_16x16x32_bf16 v[18:21], v[244:247], v[86:89], v[18:21]
	v_mfma_f32_16x16x32_bf16 v[30:33], v[216:219], v[78:81], v[30:33]
	v_mfma_f32_16x16x32_bf16 v[26:29], v[216:219], v[90:93], v[26:29]
	v_mfma_f32_16x16x32_bf16 v[22:25], v[248:251], v[78:81], v[22:25]
	v_mfma_f32_16x16x32_bf16 v[18:21], v[248:251], v[90:93], v[18:21]
	s_waitcnt lgkmcnt(0)
	v_mfma_f32_16x16x32_bf16 v[10:13], v[94:97], v[74:77], v[10:13]
	v_mfma_f32_16x16x32_bf16 v[14:17], v[94:97], v[86:89], v[14:17]
	v_mfma_f32_16x16x32_bf16 v[6:9], v[102:105], v[74:77], v[6:9]
	v_mfma_f32_16x16x32_bf16 v[2:5], v[102:105], v[86:89], v[2:5]
	v_mfma_f32_16x16x32_bf16 v[10:13], v[98:101], v[78:81], v[10:13]
	v_mfma_f32_16x16x32_bf16 v[14:17], v[98:101], v[90:93], v[14:17]
	v_mfma_f32_16x16x32_bf16 v[6:9], v[134:137], v[78:81], v[6:9]
	v_mfma_f32_16x16x32_bf16 v[2:5], v[134:137], v[90:93], v[2:5]
	s_setprio 0
	s_bitcmp1_b32 s0, 0
	s_cselect_b32 s1, 0x4400, 0
	v_add_u32_e32 v0, s1, v150
	v_add_u32_e32 v74, v0, v132
	v_add_u32_e32 v75, v74, v131
	v_add_u32_e32 v74, v74, v127
	s_cmpk_lg_i32 s0, 0x43
	v_add3_u32 v0, v0, v114, v128
	s_waitcnt vmcnt(4)
	ds_write_b128 v74, v[58:61]
	ds_write_b128 v0, v[62:65] offset:8192
	ds_write_b128 v75, v[66:69]
	ds_write_b128 v0, v[70:73] offset:12800
	s_waitcnt lgkmcnt(0)
	s_barrier
	s_cbranch_scc0 .LBB0_1282
	v_mov_b64_e32 v[122:123], v[118:119]
	s_branch .Lga_odd
.Lga_odd:
	s_bitcmp1_b32 s0, 0
	s_mov_b32 s1, s0
	s_cselect_b32 s2, 0x4400, 0
	s_add_i32 s0, s0, 1
	s_add_i32 s1, s0, 1
	s_min_u32 s1, s1, 0x43
	v_lshl_or_b32 v68, s1, 6, v126
	v_lshlrev_b32_e32 v0, 8, v68
	s_lshl_b32 s56, s1, 7
	v_lshl_add_u64 v[58:59], v[116:117], 0, v[0:1]
	v_lshl_add_u64 v[66:67], v[120:121], 0, s[56:57]
	v_or_b32_e32 v0, 32, v68
	s_mov_b32 s1, 0x44000
	v_lshlrev_b64 v[68:69], 8, v[0:1]
	v_add_co_u32_e32 v70, vcc, s1, v66
	v_lshl_add_u64 v[68:69], v[116:117], 0, v[68:69]
	s_nop 0
	v_addc_co_u32_e32 v71, vcc, 0, v67, vcc
	global_load_dwordx4 v[58:61], v[58:59], off
	s_nop 0
	global_load_dwordx4 v[62:65], v[66:67], off
	s_nop 0
	global_load_dwordx4 v[66:69], v[68:69], off
	s_nop 0
	global_load_dwordx4 v[70:73], v[70:71], off
	v_add_u32_e32 v0, s2, v150
	s_setprio 1
	v_add_u32_e32 v86, v0, v115
	v_add_u32_e32 v102, v86, v130
	ds_read_b128 v[74:77], v102
	ds_read_b128 v[82:85], v102 offset:2048
	v_add_u32_e32 v103, v86, v129
	ds_read_b128 v[86:89], v103
	ds_read_b128 v[98:101], v103 offset:2048
	s_waitcnt lgkmcnt(0)
	v_mfma_f32_16x16x32_bf16 v[78:81], v[74:77], v[46:49], 0
	v_mfma_f32_16x16x32_bf16 v[74:77], v[74:77], v[50:53], 0
	v_mfma_f32_16x16x32_bf16 v[94:97], v[86:89], v[42:45], v[78:81]
	v_mfma_f32_16x16x32_bf16 v[78:81], v[86:89], v[54:57], v[74:77]
	v_mfma_f32_16x16x32_bf16 v[74:77], v[82:85], v[46:49], 0
	v_mfma_f32_16x16x32_bf16 v[90:93], v[98:101], v[42:45], v[74:77]
	v_mfma_f32_16x16x32_bf16 v[74:77], v[82:85], v[50:53], 0
	ds_read_b128 v[82:85], v102 offset:4096
	ds_read_b128 v[134:137], v102 offset:6144
	v_mfma_f32_16x16x32_bf16 v[74:77], v[98:101], v[54:57], v[74:77]
	ds_read_b128 v[98:101], v103 offset:4096
	ds_read_b128 v[138:141], v103 offset:6144
	s_waitcnt lgkmcnt(0)
	v_add3_u32 v118, v0, v109, v112
	v_add_u32_e32 v119, 0x2000, v118
	v_add_u32_e32 v124, 0x2800, v118
	ds_read2_b64 v[212:215], v119 offset1:4
	ds_read2_b64 v[216:219], v119 offset0:8 offset1:12
	ds_read2_b64 v[244:247], v124 offset0:32 offset1:36
	ds_read2_b64 v[248:251], v124 offset0:40 offset1:44
	v_mfma_f32_16x16x32_bf16 v[86:89], v[82:85], v[46:49], 0
	v_mfma_f32_16x16x32_bf16 v[82:85], v[82:85], v[50:53], 0
	v_mfma_f32_16x16x32_bf16 v[102:105], v[98:101], v[42:45], v[86:89]
	v_mfma_f32_16x16x32_bf16 v[86:89], v[98:101], v[54:57], v[82:85]
	v_mfma_f32_16x16x32_bf16 v[82:85], v[134:137], v[46:49], 0
	v_mfma_f32_16x16x32_bf16 v[98:101], v[138:141], v[42:45], v[82:85]
	v_mfma_f32_16x16x32_bf16 v[82:85], v[134:137], v[50:53], 0
	v_mfma_f32_16x16x32_bf16 v[82:85], v[138:141], v[54:57], v[82:85]
	s_setprio 0
	v_max_f32_e32 v118, v95, v95
	v_max_f32_e32 v119, v94, v94
	v_max_f32_e32 v118, v119, v118
	v_max_f32_e32 v119, v97, v97
	v_max_f32_e32 v124, v96, v96
	v_max_f32_e32 v119, v124, v119
	v_max_f32_e32 v124, v93, v93
	v_max_f32_e32 v125, v92, v92
	v_max_f32_e32 v124, v125, v124
	v_max3_f32 v124, v90, v91, v124
	v_max3_f32 v118, v118, v119, v124
	v_max_f32_e32 v119, v105, v105
	v_max_f32_e32 v124, v104, v104
	v_max_f32_e32 v119, v124, v119
	v_max_f32_e32 v124, v101, v101
	v_max_f32_e32 v125, v100, v100
	v_max_f32_e32 v124, v125, v124
	v_max3_f32 v119, v102, v103, v119
	v_max3_f32 v124, v98, v99, v124
	v_max3_f32 v118, v118, v119, v124
	ds_bpermute_b32 v119, v111, v118
	s_waitcnt lgkmcnt(0)
	v_max_f32_e32 v119, v119, v119
	v_max_f32_e32 v118, v118, v119
	ds_bpermute_b32 v119, v113, v118
	s_waitcnt lgkmcnt(0)
	v_max_f32_e32 v119, v119, v119
	v_max_f32_e32 v118, v118, v119
	v_add_f32_e32 v119, 0x41000000, v122
	v_cmp_gt_f32_e32 vcc, v118, v119
	s_cbranch_vccz .Lga_o_1277
	v_max_f32_e32 v118, v118, v118
	v_max_f32_e32 v119, v122, v122
	v_max_f32_e32 v124, v119, v118
	v_sub_f32_e32 v118, v122, v124
	v_exp_f32_e32 v118, v118
	v_mov_b32_e32 v125, v123
	v_mov_b32_e32 v122, v124
	v_pk_mul_f32 v[38:39], v[38:39], v[118:119] op_sel_hi:[1,0]
	v_pk_mul_f32 v[40:41], v[40:41], v[118:119] op_sel_hi:[1,0]
	v_pk_mul_f32 v[32:33], v[32:33], v[118:119] op_sel_hi:[1,0]
	v_pk_mul_f32 v[30:31], v[30:31], v[118:119] op_sel_hi:[1,0]
	v_pk_mul_f32 v[24:25], v[24:25], v[118:119] op_sel_hi:[1,0]
	v_pk_mul_f32 v[22:23], v[22:23], v[118:119] op_sel_hi:[1,0]
	v_pk_mul_f32 v[12:13], v[12:13], v[118:119] op_sel_hi:[1,0]
	v_pk_mul_f32 v[10:11], v[10:11], v[118:119] op_sel_hi:[1,0]
	v_pk_mul_f32 v[8:9], v[8:9], v[118:119] op_sel_hi:[1,0]
	v_pk_mul_f32 v[6:7], v[6:7], v[118:119] op_sel_hi:[1,0]
	s_branch .Lga_o_1278

.Lga_o_1280:
	v_sub_f32_e32 v74, v74, v125
	v_exp_f32_e32 v134, v74
	v_sub_f32_e32 v74, v75, v125
	v_exp_f32_e32 v135, v74
	v_sub_f32_e32 v74, v76, v125
	v_exp_f32_e32 v136, v74
	v_sub_f32_e32 v74, v77, v125
	v_exp_f32_e32 v137, v74
	v_sub_f32_e32 v74, v86, v125
	v_exp_f32_e32 v138, v74
	v_sub_f32_e32 v74, v87, v125
	v_exp_f32_e32 v139, v74
	v_sub_f32_e32 v74, v88, v125
	v_exp_f32_e32 v140, v74
	v_sub_f32_e32 v74, v89, v125
	v_sub_f32_e32 v78, v78, v125
	v_exp_f32_e32 v141, v74
	v_sub_f32_e32 v74, v82, v125
	v_sub_f32_e32 v94, v94, v122
	v_sub_f32_e32 v95, v95, v122
	v_sub_f32_e32 v96, v96, v122
	v_sub_f32_e32 v97, v97, v122
	v_sub_f32_e32 v90, v90, v122
	v_sub_f32_e32 v91, v91, v122
	v_sub_f32_e32 v92, v92, v122
	v_sub_f32_e32 v93, v93, v122
	v_sub_f32_e32 v102, v102, v122
	v_sub_f32_e32 v103, v103, v122
	v_sub_f32_e32 v104, v104, v122
	v_sub_f32_e32 v105, v105, v122
	v_sub_f32_e32 v98, v98, v122
	v_sub_f32_e32 v99, v99, v122
	v_sub_f32_e32 v100, v100, v122
	v_sub_f32_e32 v101, v101, v122
	v_exp_f32_e32 v122, v78
	v_sub_f32_e32 v78, v79, v125
	v_exp_f32_e32 v142, v74
	v_sub_f32_e32 v74, v83, v125
	v_exp_f32_e32 v123, v78
	v_sub_f32_e32 v78, v80, v125
	v_exp_f32_e32 v143, v74
	v_sub_f32_e32 v74, v84, v125
	s_mov_b32 s38, s36
	s_mov_b32 s39, s36
	v_mov_b64_e32 v[118:119], v[124:125]
	v_exp_f32_e32 v124, v78
	v_sub_f32_e32 v78, v81, v125
	v_exp_f32_e32 v144, v74
	v_sub_f32_e32 v74, v85, v125
	s_mov_b32 s37, s36
	v_mov_b64_e32 v[84:85], s[38:39]
	v_exp_f32_e32 v94, v94
	v_exp_f32_e32 v95, v95
	v_exp_f32_e32 v96, v96
	v_exp_f32_e32 v97, v97
	v_exp_f32_e32 v90, v90
	v_exp_f32_e32 v91, v91
	v_exp_f32_e32 v92, v92
	v_exp_f32_e32 v93, v93
	v_exp_f32_e32 v133, v78
	v_mov_b64_e32 v[82:83], s[36:37]
	v_exp_f32_e32 v102, v102
	v_exp_f32_e32 v103, v103
	v_exp_f32_e32 v104, v104
	v_exp_f32_e32 v105, v105
	v_exp_f32_e32 v98, v98
	v_exp_f32_e32 v99, v99
	v_exp_f32_e32 v100, v100
	v_exp_f32_e32 v101, v101
	v_exp_f32_e32 v125, v74
	v_cvt_pk_bf16_f32 v74, v94, v95
	v_cvt_pk_bf16_f32 v75, v96, v97
	v_cvt_pk_bf16_f32 v76, v90, v91
	v_cvt_pk_bf16_f32 v77, v92, v93
	v_cvt_pk_bf16_f32 v86, v122, v123
	v_cvt_pk_bf16_f32 v87, v124, v133
	v_cvt_pk_bf16_f32 v88, v134, v135
	v_cvt_pk_bf16_f32 v89, v136, v137
	v_mfma_f32_16x16x32_bf16 v[38:41], v[82:85], v[74:77], v[38:41]
	v_cvt_pk_bf16_f32 v78, v102, v103
	v_cvt_pk_bf16_f32 v79, v104, v105
	v_cvt_pk_bf16_f32 v80, v98, v99
	v_mfma_f32_16x16x32_bf16 v[34:37], v[82:85], v[86:89], v[34:37]
	v_cvt_pk_bf16_f32 v81, v100, v101
	v_cvt_pk_bf16_f32 v90, v138, v139
	v_cvt_pk_bf16_f32 v91, v140, v141
	v_cvt_pk_bf16_f32 v92, v142, v143
	v_cvt_pk_bf16_f32 v93, v144, v125
	v_mfma_f32_16x16x32_bf16 v[38:41], v[82:85], v[78:81], v[38:41]
	s_nop 0
	v_mfma_f32_16x16x32_bf16 v[34:37], v[82:85], v[90:93], v[34:37]
	s_setprio 1
	v_add3_u32 v124, v0, v109, v112
	v_add_u32_e32 v125, 0x3000, v124
	v_add_u32_e32 v124, 0x3800, v124
	ds_read2_b64 v[94:97], v125 offset0:64 offset1:68
	ds_read2_b64 v[98:101], v125 offset0:72 offset1:76
	ds_read2_b64 v[102:105], v124 offset0:96 offset1:100
	ds_read2_b64 v[134:137], v124 offset0:104 offset1:108
	s_waitcnt lgkmcnt(4)
	v_mfma_f32_16x16x32_bf16 v[30:33], v[212:215], v[74:77], v[30:33]
	v_mfma_f32_16x16x32_bf16 v[26:29], v[212:215], v[86:89], v[26:29]
	v_mfma_f32_16x16x32_bf16 v[22:25], v[244:247], v[74:77], v[22:25]
	v_mfma_f32_16x16x32_bf16 v[18:21], v[244:247], v[86:89], v[18:21]
	v_mfma_f32_16x16x32_bf16 v[30:33], v[216:219], v[78:81], v[30:33]
	v_mfma_f32_16x16x32_bf16 v[26:29], v[216:219], v[90:93], v[26:29]
	v_mfma_f32_16x16x32_bf16 v[22:25], v[248:251], v[78:81], v[22:25]
	v_mfma_f32_16x16x32_bf16 v[18:21], v[248:251], v[90:93], v[18:21]
	s_waitcnt lgkmcnt(0)
	v_mfma_f32_16x16x32_bf16 v[10:13], v[94:97], v[74:77], v[10:13]
	v_mfma_f32_16x16x32_bf16 v[14:17], v[94:97], v[86:89], v[14:17]
	v_mfma_f32_16x16x32_bf16 v[6:9], v[102:105], v[74:77], v[6:9]
	v_mfma_f32_16x16x32_bf16 v[2:5], v[102:105], v[86:89], v[2:5]
	v_mfma_f32_16x16x32_bf16 v[10:13], v[98:101], v[78:81], v[10:13]
	v_mfma_f32_16x16x32_bf16 v[14:17], v[98:101], v[90:93], v[14:17]
	v_mfma_f32_16x16x32_bf16 v[6:9], v[134:137], v[78:81], v[6:9]
	v_mfma_f32_16x16x32_bf16 v[2:5], v[134:137], v[90:93], v[2:5]
	s_setprio 0
	s_bitcmp1_b32 s0, 0
	s_cselect_b32 s1, 0x4400, 0
	v_add_u32_e32 v0, s1, v150
	v_add_u32_e32 v74, v0, v132
	v_add_u32_e32 v75, v74, v131
	v_add_u32_e32 v74, v74, v127
	s_cmpk_lg_i32 s0, 0x43
	v_add3_u32 v0, v0, v114, v128
	s_waitcnt vmcnt(4)
	ds_write_b128 v74, v[228:231]
	ds_write_b128 v0, v[232:235] offset:8192
	ds_write_b128 v75, v[236:239]
	ds_write_b128 v0, v[240:243] offset:12800
	s_waitcnt lgkmcnt(0)
	s_barrier
	s_cbranch_scc0 .LBB0_1282
	v_mov_b64_e32 v[122:123], v[118:119]
	s_branch .LBB0_1275
.LBB0_1282:
	s_waitcnt vmcnt(0)
	s_setprio 1
	v_add_u32_e32 v0, v150, v115
	v_add_u32_e32 v86, v0, v130
	ds_read_b128 v[58:61], v86 offset:17408
	v_add_u32_e32 v0, v0, v129
	ds_read_b128 v[66:69], v0 offset:17408
	s_waitcnt lgkmcnt(1)
	v_mfma_f32_16x16x32_bf16 v[62:65], v[58:61], v[46:49], 0
	v_mfma_f32_16x16x32_bf16 v[58:61], v[58:61], v[50:53], 0
	s_waitcnt lgkmcnt(0)
	v_mfma_f32_16x16x32_bf16 v[62:65], v[66:69], v[42:45], v[62:65]
	v_mfma_f32_16x16x32_bf16 v[58:61], v[66:69], v[54:57], v[58:61]
	ds_read_b128 v[66:69], v86 offset:19456
	ds_read_b128 v[70:73], v0 offset:19456
	s_waitcnt lgkmcnt(1)
	v_mfma_f32_16x16x32_bf16 v[74:77], v[66:69], v[46:49], 0
	v_mfma_f32_16x16x32_bf16 v[66:69], v[66:69], v[50:53], 0
	s_waitcnt lgkmcnt(0)
	v_mfma_f32_16x16x32_bf16 v[78:81], v[70:73], v[42:45], v[74:77]
	v_mfma_f32_16x16x32_bf16 v[70:73], v[70:73], v[54:57], v[66:69]
	s_nop 4
	ds_read_b128 v[66:69], v86 offset:21504
	ds_read_b128 v[82:85], v0 offset:21504
	s_waitcnt lgkmcnt(1)
	v_mfma_f32_16x16x32_bf16 v[74:77], v[66:69], v[46:49], 0
	v_mfma_f32_16x16x32_bf16 v[66:69], v[66:69], v[50:53], 0
	s_waitcnt lgkmcnt(0)
	v_mfma_f32_16x16x32_bf16 v[74:77], v[82:85], v[42:45], v[74:77]
	v_mfma_f32_16x16x32_bf16 v[66:69], v[82:85], v[54:57], v[66:69]
	ds_read_b128 v[82:85], v86 offset:23552
	ds_read_b128 v[86:89], v0 offset:23552
	s_waitcnt lgkmcnt(1)
	v_mfma_f32_16x16x32_bf16 v[46:49], v[82:85], v[46:49], 0
	s_waitcnt lgkmcnt(0)
	v_mfma_f32_16x16x32_bf16 v[46:49], v[86:89], v[42:45], v[46:49]
	v_mfma_f32_16x16x32_bf16 v[42:45], v[82:85], v[50:53], 0
	v_mfma_f32_16x16x32_bf16 v[42:45], v[86:89], v[54:57], v[42:45]
	s_setprio 0
	v_max_f32_e32 v0, v63, v63
	v_max_f32_e32 v50, v62, v62
	v_max_f32_e32 v0, v50, v0
	v_max_f32_e32 v50, v65, v65
	v_max_f32_e32 v51, v64, v64
	v_max_f32_e32 v50, v51, v50
	v_max_f32_e32 v51, v81, v81
	v_max_f32_e32 v52, v80, v80
	v_max_f32_e32 v51, v52, v51
	v_max3_f32 v51, v78, v79, v51
	v_max3_f32 v0, v0, v50, v51
	v_max_f32_e32 v50, v77, v77
	v_max_f32_e32 v51, v76, v76
	v_max_f32_e32 v50, v51, v50
	v_max_f32_e32 v51, v49, v49
	v_max_f32_e32 v52, v48, v48
	v_max_f32_e32 v51, v52, v51
	v_max3_f32 v50, v74, v75, v50
	v_max3_f32 v51, v46, v47, v51
	v_max3_f32 v0, v0, v50, v51
	ds_bpermute_b32 v50, v111, v0
	s_waitcnt lgkmcnt(0)
	v_max_f32_e32 v50, v50, v50
	v_max_f32_e32 v0, v0, v50
	ds_bpermute_b32 v50, v113, v0
	s_waitcnt lgkmcnt(0)
	v_max_f32_e32 v50, v50, v50
	v_max_f32_e32 v0, v0, v50
	v_add_f32_e32 v50, 0x41000000, v118
	v_cmp_gt_f32_e32 vcc, v0, v50
	s_cbranch_vccz .LBB0_1284
	v_max_f32_e32 v0, v0, v0
	v_max_f32_e32 v50, v118, v118
	v_max_f32_e32 v50, v50, v0
	v_sub_f32_e32 v0, v118, v50
	v_exp_f32_e32 v0, v0
	v_mov_b32_e32 v118, v50
	v_pk_mul_f32 v[38:39], v[38:39], v[0:1] op_sel_hi:[1,0]
	v_pk_mul_f32 v[40:41], v[40:41], v[0:1] op_sel_hi:[1,0]
	v_pk_mul_f32 v[32:33], v[32:33], v[0:1] op_sel_hi:[1,0]
	v_pk_mul_f32 v[30:31], v[30:31], v[0:1] op_sel_hi:[1,0]
	v_pk_mul_f32 v[24:25], v[24:25], v[0:1] op_sel_hi:[1,0]
	v_pk_mul_f32 v[22:23], v[22:23], v[0:1] op_sel_hi:[1,0]
	v_pk_mul_f32 v[12:13], v[12:13], v[0:1] op_sel_hi:[1,0]
	v_pk_mul_f32 v[10:11], v[10:11], v[0:1] op_sel_hi:[1,0]
	v_pk_mul_f32 v[8:9], v[8:9], v[0:1] op_sel_hi:[1,0]
	v_pk_mul_f32 v[6:7], v[6:7], v[0:1] op_sel_hi:[1,0]
